# QK-norm reductions in the K/V conversion pass use DPP adds (quad_perm, row_half_mirror) instead of three ds_bpermute round trips each
# speedup vs baseline: 1.0063x; 1.0063x over previous
; __device__ __forceinline__ unsigned cvt_pk_bf16(float lo, float hi) { unsigned r; asm volatile("v_cvt_pk_bf16_f32 %0, %1, %2" : "=v"(r) : "v"(lo), "v"(hi)); return r; }
; __device__ __forceinline__ float bf_lo(unsigned v) { return __uint_as_float(v << 16); }
; __device__ __forceinline__ float bf_hi(unsigned v) { return __uint_as_float(v & 0xffff0000u); }
; __global__ void __launch_bounds__(512, 2) mega(Params p) {
;     ...
;             for (int t = gw; t < S_; t += ngw) {
; #pragma unroll
;                 for (int which = 0; which < 2; ++which) {
;                     u32x4* ptr = (u32x4*)(Z + (size_t)t * ZLD + (which ? OFF_K : OFF_Q) + lane * 16);
;                     const u32x4 a = ptr[0], b = ptr[1];
;                     float f[16] = {bf_lo(a.x), bf_hi(a.x), bf_lo(a.y), bf_hi(a.y), bf_lo(a.z), bf_hi(a.z), bf_lo(a.w), bf_hi(a.w), bf_lo(b.x), bf_hi(b.x), bf_lo(b.y), bf_hi(b.y), bf_lo(b.z), bf_hi(b.z), bf_lo(b.w), bf_hi(b.w)};
;                     float ss = 0.f;
; #pragma unroll
;                     for (int e = 0; e < 16; ++e) ss = fmaf(f[e], f[e], ss);
;                     ss += __shfl_xor(ss, 1); ss += __shfl_xor(ss, 2); ss += __shfl_xor(ss, 4);
;                     const float rinv = 1.f / sqrtf(ss * (1.f / 128.f) + EPS_);
; #pragma unroll
;                     for (int e = 0; e < 16; ++e) f[e] = f[e] * rinv * (which ? 1.f : gq[e]);
;                     if (which == 0) {
;                         u32x4 oa, ob; oa.x = cvt_pk_bf16(f[0], f[1]); oa.y = cvt_pk_bf16(f[2], f[3]); oa.z = cvt_pk_bf16(f[4], f[5]); oa.w = cvt_pk_bf16(f[6], f[7]);
;                         ob.x = cvt_pk_bf16(f[8], f[9]); ob.y = cvt_pk_bf16(f[10], f[11]); ob.z = cvt_pk_bf16(f[12], f[13]); ob.w = cvt_pk_bf16(f[14], f[15]);
;                         ptr[0] = oa; ptr[1] = ob;
.LBB0_1175:
	v_lshl_add_u64 v[8:9], s[60:61], 0, v[4:5]
	s_mov_b64 s[6:7], 0xa000800
	v_add_co_u32_e32 v48, vcc, 0xa000000, v8
	v_lshl_add_u64 v[36:37], v[8:9], 0, s[6:7]
	s_nop 0
	v_addc_co_u32_e32 v49, vcc, 0, v9, vcc
	global_load_dwordx4 v[32:35], v[48:49], off offset:2048
	s_nop 0
	global_load_dwordx4 v[36:39], v[36:37], off offset:16
	s_mov_b64 s[12:13], 0xa001000
	v_lshl_add_u64 v[164:165], v[8:9], 0, s[12:13]
	global_load_dwordx4 v[148:151], v[164:165], off
	global_load_dwordx4 v[152:155], v[164:165], off offset:16
	global_load_dwordx4 v[156:159], v[164:165], off offset:2048
	global_load_dwordx4 v[160:163], v[164:165], off offset:2064
	s_mov_b32 s4, 0xa001000
	v_add_co_u32_e64 v50, s[6:7], s4, v8
	s_mov_b64 s[8:9], 0xa001000
	s_nop 0
	v_addc_co_u32_e64 v51, s[6:7], 0, v9, s[6:7]
	v_lshl_add_u64 v[44:45], v[8:9], 0, s[8:9]
	v_lshl_add_u64 v[10:11], s[60:61], 0, v[6:7]
	v_and_b32_e32 v166, 0xfffff800, v6
	v_lshrrev_b32_e32 v166, 3, v166
	v_and_b32_e32 v167, 0x7f, v6
	v_add_u32_e32 v166, v166, v167
	v_bfe_u32 v167, v6, 7, 3
	v_lshl_add_u32 v166, v167, 22, v166
	v_mov_b32_e32 v167, 0
	v_lshl_add_u64 v[166:167], s[60:61], 0, v[166:167]
	s_mov_b64 s[14:15], 0x1b800000
	v_lshl_add_u64 v[166:167], v[166:167], 0, s[14:15]
	v_mov_b32_e32 v0, 0
	v_mov_b32_e32 v1, 0
	v_mov_b32_e32 v2, 0
	v_mov_b32_e32 v3, 0
	s_add_i32 s10, s10, s82
	v_lshl_add_u64 v[6:7], v[6:7], 0, s[50:51]
	v_lshl_add_u64 v[4:5], v[4:5], 0, s[52:53]
	s_cmpk_gt_i32 s10, 0x3fff
	s_waitcnt vmcnt(5)
	v_lshlrev_b32_e32 v31, 16, v32
	v_and_b32_e32 v32, 0xffff0000, v32
	v_fma_f32 v53, v31, v31, 0
	v_lshlrev_b32_e32 v40, 16, v33
	v_fmac_f32_e32 v53, v32, v32
	v_and_b32_e32 v33, 0xffff0000, v33
	v_fmac_f32_e32 v53, v40, v40
	v_lshlrev_b32_e32 v41, 16, v34
	v_fmac_f32_e32 v53, v33, v33
	v_and_b32_e32 v34, 0xffff0000, v34
	v_fmac_f32_e32 v53, v41, v41
	v_lshlrev_b32_e32 v42, 16, v35
	v_fmac_f32_e32 v53, v34, v34
	v_and_b32_e32 v35, 0xffff0000, v35
	v_fmac_f32_e32 v53, v42, v42
	s_waitcnt vmcnt(4)
	v_lshlrev_b32_e32 v43, 16, v36
	v_fmac_f32_e32 v53, v35, v35
	v_and_b32_e32 v36, 0xffff0000, v36
	v_fmac_f32_e32 v53, v43, v43
	v_lshlrev_b32_e32 v46, 16, v37
	v_fmac_f32_e32 v53, v36, v36
	v_and_b32_e32 v37, 0xffff0000, v37
	v_fmac_f32_e32 v53, v46, v46
	v_lshlrev_b32_e32 v47, 16, v38
	v_fmac_f32_e32 v53, v37, v37
	v_and_b32_e32 v38, 0xffff0000, v38
	v_fmac_f32_e32 v53, v47, v47
	v_lshlrev_b32_e32 v52, 16, v39
	v_fmac_f32_e32 v53, v38, v38
	v_and_b32_e32 v39, 0xffff0000, v39
	v_fmac_f32_e32 v53, v52, v52
	v_fmac_f32_e32 v53, v39, v39
	s_nop 1
	v_add_f32_dpp v53, v53, v53 quad_perm:[1,0,3,2] row_mask:0xf bank_mask:0xf
	s_nop 1
	v_add_f32_dpp v53, v53, v53 quad_perm:[2,3,0,1] row_mask:0xf bank_mask:0xf
	s_nop 1
	v_add_f32_dpp v53, v53, v53 row_half_mirror row_mask:0xf bank_mask:0xf
	v_fmamk_f32 v53, v53, 0x3c000000, v121
	v_mul_f32_e32 v54, 0x4f800000, v53
	v_cmp_gt_f32_e32 vcc, s39, v53
	s_nop 1
	v_cndmask_b32_e32 v53, v53, v54, vcc
	v_sqrt_f32_e32 v54, v53
	s_nop 0
	v_add_u32_e32 v55, -1, v54
	v_add_u32_e32 v56, 1, v54
	v_fma_f32 v57, -v55, v54, v53
	v_fma_f32 v58, -v56, v54, v53
	v_cmp_ge_f32_e64 s[6:7], 0, v57
	s_nop 1
	v_cndmask_b32_e64 v54, v54, v55, s[6:7]
	v_cmp_lt_f32_e64 s[6:7], 0, v58
	s_nop 1
	v_cndmask_b32_e64 v54, v54, v56, s[6:7]
	v_mul_f32_e32 v55, 0x37800000, v54
	v_cndmask_b32_e32 v54, v54, v55, vcc
	v_cmp_class_f32_e32 vcc, v53, v122
	s_mov_b32 s6, 0x1b800000
	s_nop 0
	v_cndmask_b32_e32 v53, v54, v53, vcc
	v_div_scale_f32 v54, s[4:5], v53, v53, 1.0
	v_rcp_f32_e32 v56, v54
	v_div_scale_f32 v55, vcc, 1.0, v53, 1.0
	s_mov_b64 s[4:5], 0xa001800
	v_fma_f32 v57, -v54, v56, 1.0
	v_fmac_f32_e32 v56, v57, v56
	v_mul_f32_e32 v57, v55, v56
	v_fma_f32 v58, -v54, v57, v55
	v_fmac_f32_e32 v57, v58, v56
	v_fma_f32 v54, -v54, v57, v55
	v_div_fmas_f32 v54, v54, v56, v57
	v_div_fixup_f32 v53, v54, v53, 1.0
	v_mul_f32_e32 v39, v53, v39
	v_mul_f32_e32 v38, v53, v38
	v_mul_f32_e32 v47, v53, v47
	v_mul_f32_e32 v37, v53, v37
	v_mul_f32_e32 v46, v53, v46
	v_mul_f32_e32 v36, v53, v36
	v_mul_f32_e32 v43, v53, v43
	v_mul_f32_e32 v35, v53, v35
	v_mul_f32_e32 v42, v53, v42
	v_mul_f32_e32 v34, v53, v34
	v_mul_f32_e32 v41, v53, v41
	v_mul_f32_e32 v33, v53, v33
	v_mul_f32_e32 v40, v53, v40
	v_mul_f32_e32 v32, v53, v32
	v_mul_f32_e32 v52, v53, v52
	v_mul_f32_e32 v31, v53, v31
	v_mul_f32_e32 v39, v39, v30
	v_mul_f32_e32 v38, v38, v28
	v_mul_f32_e32 v47, v47, v27
	v_mul_f32_e32 v37, v37, v26
	v_mul_f32_e32 v46, v46, v25
	v_mul_f32_e32 v36, v36, v24
	v_mul_f32_e32 v43, v43, v23
	v_mul_f32_e32 v35, v35, v22
	v_mul_f32_e32 v42, v42, v21
	v_mul_f32_e32 v34, v34, v20
	v_mul_f32_e32 v41, v41, v19
	v_mul_f32_e32 v33, v33, v18
	v_mul_f32_e32 v40, v40, v17
	v_mul_f32_e32 v32, v32, v16
	v_mul_f32_e32 v52, v52, v29
	v_mul_f32_e32 v31, v31, v15
	v_cvt_pk_bf16_f32 v32, v31, v32
	v_cvt_pk_bf16_f32 v33, v40, v33
	v_cvt_pk_bf16_f32 v34, v41, v34
	v_cvt_pk_bf16_f32 v35, v42, v35
	v_cvt_pk_bf16_f32 v36, v43, v36
	v_cvt_pk_bf16_f32 v37, v46, v37
	v_cvt_pk_bf16_f32 v38, v47, v38
	v_cvt_pk_bf16_f32 v39, v52, v39
	s_waitcnt vmcnt(2)
; __device__ __forceinline__ float bf_lo(unsigned v) { return __uint_as_float(v << 16); }
; __device__ __forceinline__ float bf_hi(unsigned v) { return __uint_as_float(v & 0xffff0000u); }
; __global__ void __launch_bounds__(512, 2) mega(Params p) {
;     ...
;                     } else {
;                         int w0 = 0, w1 = 0, w2 = 0, w3 = 0;
;                         w0 = __builtin_amdgcn_cvt_pk_fp8_f32(f[0], f[1], w0, false); w0 = __builtin_amdgcn_cvt_pk_fp8_f32(f[2], f[3], w0, true);
;                         w1 = __builtin_amdgcn_cvt_pk_fp8_f32(f[4], f[5], w1, false); w1 = __builtin_amdgcn_cvt_pk_fp8_f32(f[6], f[7], w1, true);
;                         w2 = __builtin_amdgcn_cvt_pk_fp8_f32(f[8], f[9], w2, false); w2 = __builtin_amdgcn_cvt_pk_fp8_f32(f[10], f[11], w2, true);
;                         w3 = __builtin_amdgcn_cvt_pk_fp8_f32(f[12], f[13], w3, false); w3 = __builtin_amdgcn_cvt_pk_fp8_f32(f[14], f[15], w3, true);
;                         u32x4 o8; o8.x = (unsigned)w0; o8.y = (unsigned)w1; o8.z = (unsigned)w2; o8.w = (unsigned)w3;
;                         *(u32x4*)(KV8 + (size_t)t * 2048 + lane * 16) = o8;
;                     }
;                 }
;                 {
;                     const u32x4* ptr = (const u32x4*)(Z + (size_t)t * ZLD + OFF_V + lane * 16);
;                     const u32x4 a = ptr[0], b = ptr[1];
;                     int w0 = 0, w1 = 0, w2 = 0, w3 = 0;
;                     w0 = __builtin_amdgcn_cvt_pk_fp8_f32(bf_lo(a.x), bf_hi(a.x), w0, false); w0 = __builtin_amdgcn_cvt_pk_fp8_f32(bf_lo(a.y), bf_hi(a.y), w0, true);
;                     w1 = __builtin_amdgcn_cvt_pk_fp8_f32(bf_lo(a.z), bf_hi(a.z), w1, false); w1 = __builtin_amdgcn_cvt_pk_fp8_f32(bf_lo(a.w), bf_hi(a.w), w1, true);
;                     w2 = __builtin_amdgcn_cvt_pk_fp8_f32(bf_lo(b.x), bf_hi(b.x), w2, false); w2 = __builtin_amdgcn_cvt_pk_fp8_f32(bf_lo(b.y), bf_hi(b.y), w2, true);
;                     w3 = __builtin_amdgcn_cvt_pk_fp8_f32(bf_lo(b.z), bf_hi(b.z), w3, false); w3 = __builtin_amdgcn_cvt_pk_fp8_f32(bf_lo(b.w), bf_hi(b.w), w3, true);
;                     u32x4 o8; o8.x = (unsigned)w0; o8.y = (unsigned)w1; o8.z = (unsigned)w2; o8.w = (unsigned)w3;
;                     *(u32x4*)(KV8 + (size_t)t * 2048 + 1024 + lane * 16) = o8;
;                 }
	v_mov_b32_e32 v40, v148
	v_mov_b32_e32 v41, v149
	v_mov_b32_e32 v42, v150
	v_mov_b32_e32 v43, v151
	s_nop 0
	v_mov_b32_e32 v44, v152
	v_mov_b32_e32 v45, v153
	v_mov_b32_e32 v46, v154
	v_mov_b32_e32 v47, v155
	v_add_co_u32_e32 v52, vcc, s6, v10
	global_store_dwordx4 v[48:49], v[32:35], off offset:2048
	global_store_dwordx4 v[48:49], v[36:39], off offset:2064
	v_addc_co_u32_e32 v53, vcc, 0, v11, vcc
	v_lshl_add_u64 v[8:9], v[8:9], 0, s[4:5]
	v_lshlrev_b32_e32 v10, 16, v40
	v_and_b32_e32 v11, 0xffff0000, v40
	v_lshlrev_b32_e32 v39, 16, v45
	v_and_b32_e32 v40, 0xffff0000, v45
	v_fma_f32 v45, v10, v10, 0
	v_lshlrev_b32_e32 v31, 16, v41
	v_fmac_f32_e32 v45, v11, v11
	v_and_b32_e32 v32, 0xffff0000, v41
	v_fmac_f32_e32 v45, v31, v31
	v_lshlrev_b32_e32 v33, 16, v42
	v_fmac_f32_e32 v45, v32, v32
	v_and_b32_e32 v34, 0xffff0000, v42
	v_fmac_f32_e32 v45, v33, v33
	v_lshlrev_b32_e32 v35, 16, v43
	v_fmac_f32_e32 v45, v34, v34
	v_and_b32_e32 v36, 0xffff0000, v43
	v_fmac_f32_e32 v45, v35, v35
	v_lshlrev_b32_e32 v37, 16, v44
	v_fmac_f32_e32 v45, v36, v36
	v_and_b32_e32 v38, 0xffff0000, v44
	v_fmac_f32_e32 v45, v37, v37
	v_fmac_f32_e32 v45, v38, v38
	v_fmac_f32_e32 v45, v39, v39
	v_lshlrev_b32_e32 v41, 16, v46
	v_fmac_f32_e32 v45, v40, v40
	v_and_b32_e32 v42, 0xffff0000, v46
	v_fmac_f32_e32 v45, v41, v41
	v_lshlrev_b32_e32 v43, 16, v47
	v_fmac_f32_e32 v45, v42, v42
	v_and_b32_e32 v44, 0xffff0000, v47
	v_fmac_f32_e32 v45, v43, v43
	v_fmac_f32_e32 v45, v44, v44
	s_nop 1
	v_add_f32_dpp v45, v45, v45 quad_perm:[1,0,3,2] row_mask:0xf bank_mask:0xf
	s_nop 1
	v_add_f32_dpp v45, v45, v45 quad_perm:[2,3,0,1] row_mask:0xf bank_mask:0xf
	s_nop 1
	v_add_f32_dpp v45, v45, v45 row_half_mirror row_mask:0xf bank_mask:0xf
	v_fmamk_f32 v45, v45, 0x3c000000, v121
	v_mul_f32_e32 v46, 0x4f800000, v45
	v_cmp_gt_f32_e32 vcc, s39, v45
	s_nop 1
	v_cndmask_b32_e32 v45, v45, v46, vcc
	v_sqrt_f32_e32 v46, v45
	s_nop 0
	v_add_u32_e32 v47, -1, v46
	v_add_u32_e32 v48, 1, v46
	v_fma_f32 v49, -v47, v46, v45
	v_fma_f32 v54, -v48, v46, v45
	v_cmp_ge_f32_e64 s[6:7], 0, v49
	s_nop 1
	v_cndmask_b32_e64 v46, v46, v47, s[6:7]
	v_cmp_lt_f32_e64 s[6:7], 0, v54
	s_nop 1
	v_cndmask_b32_e64 v46, v46, v48, s[6:7]
	v_mul_f32_e32 v47, 0x37800000, v46
	v_cndmask_b32_e32 v46, v46, v47, vcc
	v_cmp_class_f32_e32 vcc, v45, v122
	s_nop 1
	v_cndmask_b32_e32 v45, v46, v45, vcc
	v_div_scale_f32 v46, s[4:5], v45, v45, 1.0
	v_rcp_f32_e32 v48, v46
	v_div_scale_f32 v47, vcc, 1.0, v45, 1.0
	v_fma_f32 v49, -v46, v48, 1.0
	v_fmac_f32_e32 v48, v49, v48
	v_mul_f32_e32 v49, v47, v48
	v_fma_f32 v54, -v46, v49, v47
	v_fmac_f32_e32 v49, v54, v48
	v_fma_f32 v46, -v46, v49, v47
	v_div_fmas_f32 v46, v46, v48, v49
	v_div_fixup_f32 v45, v46, v45, 1.0
	v_mul_f32_e32 v42, v45, v42
	v_mul_f32_e32 v41, v45, v41
	v_mul_f32_e32 v38, v45, v38
	v_mul_f32_e32 v37, v45, v37
	v_mul_f32_e32 v34, v45, v34
	v_mul_f32_e32 v33, v45, v33
	v_mul_f32_e32 v11, v45, v11
	v_mul_f32_e32 v10, v45, v10
	v_cvt_pk_fp8_f32 v0, v10, v11
	v_cvt_pk_fp8_f32 v1, v33, v34
	v_cvt_pk_fp8_f32 v2, v37, v38
	v_cvt_pk_fp8_f32 v3, v41, v42
	v_mul_f32_e32 v44, v45, v44
	v_mul_f32_e32 v43, v45, v43
	v_mul_f32_e32 v40, v45, v40
	v_mul_f32_e32 v39, v45, v39
	v_mul_f32_e32 v36, v45, v36
	v_mul_f32_e32 v35, v45, v35
	v_mul_f32_e32 v32, v45, v32
	v_mul_f32_e32 v31, v45, v31
	v_cvt_pk_fp8_f32 v0, v31, v32 op_sel:[0,0,1]
	v_cvt_pk_fp8_f32 v1, v35, v36 op_sel:[0,0,1]
	v_cvt_pk_fp8_f32 v2, v39, v40 op_sel:[0,0,1]
	v_cvt_pk_fp8_f32 v3, v43, v44 op_sel:[0,0,1]
	v_mov_b32_e32 v32, 0
	v_mov_b32_e32 v33, 0
	v_mov_b32_e32 v34, 0
	global_store_dwordx4 v[166:167], v[0:3], off
	s_waitcnt vmcnt(3)
	v_mov_b32_e32 v8, v160
	v_mov_b32_e32 v9, v161
	v_mov_b32_e32 v10, v162
	v_mov_b32_e32 v11, v163
	s_nop 0
	v_mov_b32_e32 v0, v156
	v_mov_b32_e32 v1, v157
	v_mov_b32_e32 v2, v158
	v_mov_b32_e32 v3, v159
	v_mov_b32_e32 v35, 0
	v_lshlrev_b32_e32 v31, 16, v0
	v_and_b32_e32 v0, 0xffff0000, v0
	v_lshlrev_b32_e32 v37, 16, v2
	v_and_b32_e32 v2, 0xffff0000, v2
	v_lshlrev_b32_e32 v39, 16, v8
	v_and_b32_e32 v8, 0xffff0000, v8
	v_lshlrev_b32_e32 v41, 16, v10
	v_and_b32_e32 v10, 0xffff0000, v10
	v_cvt_pk_fp8_f32 v32, v31, v0
	v_cvt_pk_fp8_f32 v33, v37, v2
	v_cvt_pk_fp8_f32 v34, v39, v8
	v_cvt_pk_fp8_f32 v35, v41, v10
	v_lshlrev_b32_e32 v36, 16, v1
	v_and_b32_e32 v1, 0xffff0000, v1
	v_lshlrev_b32_e32 v38, 16, v3
	v_and_b32_e32 v3, 0xffff0000, v3
	v_lshlrev_b32_e32 v40, 16, v9
	v_and_b32_e32 v9, 0xffff0000, v9
	v_lshlrev_b32_e32 v42, 16, v11
	v_and_b32_e32 v11, 0xffff0000, v11
	v_cvt_pk_fp8_f32 v32, v36, v1 op_sel:[0,0,1]
	v_cvt_pk_fp8_f32 v33, v38, v3 op_sel:[0,0,1]
	v_cvt_pk_fp8_f32 v34, v40, v9 op_sel:[0,0,1]
	v_cvt_pk_fp8_f32 v35, v42, v11 op_sel:[0,0,1]
	global_store_dwordx4 v[166:167], v[32:35], off offset:128
	s_cbranch_scc0 .LBB0_1175
	s_branch .LBB0_352
